# hand-written SwiGLU GEMM epilogues (packed f32 scale/add, bit-identical op order) for FFN1/FFN2 gate-up
# baseline (speedup 1.0000x reference)
; DEVINL float sigmoidf_(float z) { return __builtin_amdgcn_rcpf(1.0f + __expf(-z)); }
;     DEVINL void operator()(AccRef acc, const Unit& u, int wr, int wc, int fr, int fq) const {
;         const int row0 = u.pm * BM + wr * 64 + fr, col0 = u.pn * HALF + wc * 32 + 8 * fq;
; #pragma unroll
;         for (int ai = 0; ai < 2; ++ai)
; #pragma unroll
;             for (int m = 0; m < 4; ++m) { bf16_t* rowp = O + (size_t)(row0 + ai * HALF + m * 16) * DFF + col0;
;                 f32x4 v[2];
; #pragma unroll
;                 for (int n = 0; n < 2; ++n)
; #pragma unroll
;                     for (int j = 0; j < 4; ++j) { const float gt = acc[ai][0][m][n][j], up = acc[ai][1][m][n][j]; v[n][j] = gt * sigmoidf_(gt) * up; }
;                 store8_nt(rowp, v[0], v[1]); }
.LBB0_335:
	v_lshl_or_b32 v154, s83, 7, v148
	v_lshl_add_u32 v152, s92, 8, v146
	v_ashrrev_i32_e32 v155, 31, v154
	v_mov_b64_e32 v[144:145], s[90:91]
	v_lshlrev_b64 v[158:159], 1, v[154:155]
	s_and_b64 vcc, exec, s[4:5]
	s_mov_b32 s83, s16
	s_mov_b32 s92, s60
	s_mov_b64 s[12:13], s[62:63]
	s_mov_b32 s98, 0xbfb8aa3b
	s_mov_b32 s99, 0xbfb8aa3b
	v_mad_i64_i32 v[156:157], s[10:11], v152, s82, v[144:145]
	v_pk_mul_f32 v[160:161], v[124:125], s[98:99]
	v_pk_mul_f32 v[162:163], v[126:127], s[98:99]
	v_pk_mul_f32 v[164:165], v[116:117], s[98:99]
	v_pk_mul_f32 v[166:167], v[118:119], s[98:99]
	v_exp_f32_e32 v160, v160
	v_exp_f32_e32 v161, v161
	v_exp_f32_e32 v162, v162
	v_exp_f32_e32 v163, v163
	v_exp_f32_e32 v164, v164
	v_exp_f32_e32 v165, v165
	v_exp_f32_e32 v166, v166
	v_exp_f32_e32 v167, v167
	v_lshl_add_u64 v[156:157], v[156:157], 0, v[158:159]
	v_pk_add_f32 v[160:161], v[160:161], 1.0 op_sel_hi:[1,0]
	v_pk_add_f32 v[162:163], v[162:163], 1.0 op_sel_hi:[1,0]
	v_pk_add_f32 v[164:165], v[164:165], 1.0 op_sel_hi:[1,0]
	v_pk_add_f32 v[166:167], v[166:167], 1.0 op_sel_hi:[1,0]
	v_rcp_f32_e32 v160, v160
	v_rcp_f32_e32 v161, v161
	v_rcp_f32_e32 v162, v162
	v_rcp_f32_e32 v163, v163
	v_rcp_f32_e32 v164, v164
	v_rcp_f32_e32 v165, v165
	v_rcp_f32_e32 v166, v166
	v_rcp_f32_e32 v167, v167
	v_pk_mul_f32 v[124:125], v[124:125], v[160:161]
	v_pk_mul_f32 v[126:127], v[126:127], v[162:163]
	v_pk_mul_f32 v[116:117], v[116:117], v[164:165]
	v_pk_mul_f32 v[118:119], v[118:119], v[166:167]
	v_pk_mul_f32 v[124:125], v[120:121], v[124:125]
	v_pk_mul_f32 v[126:127], v[122:123], v[126:127]
	v_pk_mul_f32 v[116:117], v[112:113], v[116:117]
	v_pk_mul_f32 v[118:119], v[114:115], v[118:119]
	v_cvt_pk_bf16_f32 v176, v124, v125
	v_cvt_pk_bf16_f32 v177, v126, v127
	v_cvt_pk_bf16_f32 v178, v116, v117
	v_cvt_pk_bf16_f32 v179, v118, v119
	global_store_dwordx4 v[156:157], v[176:179], off nt
	v_add_u32_e32 v153, 0x10, v152
	v_mad_i64_i32 v[184:185], s[10:11], v153, s82, v[144:145]
	v_pk_mul_f32 v[168:169], v[108:109], s[98:99]
	v_pk_mul_f32 v[170:171], v[110:111], s[98:99]
	v_pk_mul_f32 v[172:173], v[100:101], s[98:99]
	v_pk_mul_f32 v[174:175], v[102:103], s[98:99]
	v_exp_f32_e32 v168, v168
	v_exp_f32_e32 v169, v169
	v_exp_f32_e32 v170, v170
	v_exp_f32_e32 v171, v171
	v_exp_f32_e32 v172, v172
	v_exp_f32_e32 v173, v173
	v_exp_f32_e32 v174, v174
	v_exp_f32_e32 v175, v175
	v_lshl_add_u64 v[184:185], v[184:185], 0, v[158:159]
	v_pk_add_f32 v[168:169], v[168:169], 1.0 op_sel_hi:[1,0]
	v_pk_add_f32 v[170:171], v[170:171], 1.0 op_sel_hi:[1,0]
	v_pk_add_f32 v[172:173], v[172:173], 1.0 op_sel_hi:[1,0]
	v_pk_add_f32 v[174:175], v[174:175], 1.0 op_sel_hi:[1,0]
	v_rcp_f32_e32 v168, v168
	v_rcp_f32_e32 v169, v169
	v_rcp_f32_e32 v170, v170
	v_rcp_f32_e32 v171, v171
	v_rcp_f32_e32 v172, v172
	v_rcp_f32_e32 v173, v173
	v_rcp_f32_e32 v174, v174
	v_rcp_f32_e32 v175, v175
	v_pk_mul_f32 v[108:109], v[108:109], v[168:169]
	v_pk_mul_f32 v[110:111], v[110:111], v[170:171]
	v_pk_mul_f32 v[100:101], v[100:101], v[172:173]
	v_pk_mul_f32 v[102:103], v[102:103], v[174:175]
	v_pk_mul_f32 v[108:109], v[104:105], v[108:109]
	v_pk_mul_f32 v[110:111], v[106:107], v[110:111]
	v_pk_mul_f32 v[100:101], v[96:97], v[100:101]
	v_pk_mul_f32 v[102:103], v[98:99], v[102:103]
	v_cvt_pk_bf16_f32 v180, v108, v109
	v_cvt_pk_bf16_f32 v181, v110, v111
	v_cvt_pk_bf16_f32 v182, v100, v101
	v_cvt_pk_bf16_f32 v183, v102, v103
	global_store_dwordx4 v[184:185], v[180:183], off nt
	v_add_u32_e32 v153, 0x20, v152
	v_mad_i64_i32 v[156:157], s[10:11], v153, s82, v[144:145]
	v_pk_mul_f32 v[160:161], v[92:93], s[98:99]
	v_pk_mul_f32 v[162:163], v[94:95], s[98:99]
	v_pk_mul_f32 v[164:165], v[84:85], s[98:99]
	v_pk_mul_f32 v[166:167], v[86:87], s[98:99]
	v_exp_f32_e32 v160, v160
	v_exp_f32_e32 v161, v161
	v_exp_f32_e32 v162, v162
	v_exp_f32_e32 v163, v163
	v_exp_f32_e32 v164, v164
	v_exp_f32_e32 v165, v165
	v_exp_f32_e32 v166, v166
	v_exp_f32_e32 v167, v167
	v_lshl_add_u64 v[156:157], v[156:157], 0, v[158:159]
	v_pk_add_f32 v[160:161], v[160:161], 1.0 op_sel_hi:[1,0]
	v_pk_add_f32 v[162:163], v[162:163], 1.0 op_sel_hi:[1,0]
	v_pk_add_f32 v[164:165], v[164:165], 1.0 op_sel_hi:[1,0]
	v_pk_add_f32 v[166:167], v[166:167], 1.0 op_sel_hi:[1,0]
	v_rcp_f32_e32 v160, v160
	v_rcp_f32_e32 v161, v161
	v_rcp_f32_e32 v162, v162
	v_rcp_f32_e32 v163, v163
	v_rcp_f32_e32 v164, v164
	v_rcp_f32_e32 v165, v165
	v_rcp_f32_e32 v166, v166
	v_rcp_f32_e32 v167, v167
	v_pk_mul_f32 v[92:93], v[92:93], v[160:161]
	v_pk_mul_f32 v[94:95], v[94:95], v[162:163]
	v_pk_mul_f32 v[84:85], v[84:85], v[164:165]
	v_pk_mul_f32 v[86:87], v[86:87], v[166:167]
	v_pk_mul_f32 v[92:93], v[88:89], v[92:93]
	v_pk_mul_f32 v[94:95], v[90:91], v[94:95]
	v_pk_mul_f32 v[84:85], v[80:81], v[84:85]
	v_pk_mul_f32 v[86:87], v[82:83], v[86:87]
	v_cvt_pk_bf16_f32 v176, v92, v93
	v_cvt_pk_bf16_f32 v177, v94, v95
	v_cvt_pk_bf16_f32 v178, v84, v85
	v_cvt_pk_bf16_f32 v179, v86, v87
	global_store_dwordx4 v[156:157], v[176:179], off nt
	v_add_u32_e32 v153, 0x30, v152
	v_mad_i64_i32 v[184:185], s[10:11], v153, s82, v[144:145]
	v_pk_mul_f32 v[168:169], v[76:77], s[98:99]
	v_pk_mul_f32 v[170:171], v[78:79], s[98:99]
	v_pk_mul_f32 v[172:173], v[68:69], s[98:99]
	v_pk_mul_f32 v[174:175], v[70:71], s[98:99]
	v_exp_f32_e32 v168, v168
	v_exp_f32_e32 v169, v169
	v_exp_f32_e32 v170, v170
	v_exp_f32_e32 v171, v171
	v_exp_f32_e32 v172, v172
	v_exp_f32_e32 v173, v173
	v_exp_f32_e32 v174, v174
	v_exp_f32_e32 v175, v175
	v_lshl_add_u64 v[184:185], v[184:185], 0, v[158:159]
	v_pk_add_f32 v[168:169], v[168:169], 1.0 op_sel_hi:[1,0]
	v_pk_add_f32 v[170:171], v[170:171], 1.0 op_sel_hi:[1,0]
; DEVINL float sigmoidf_(float z) { return __builtin_amdgcn_rcpf(1.0f + __expf(-z)); }
;     DEVINL void operator()(AccRef acc, const Unit& u, int wr, int wc, int fr, int fq) const {
;         const int row0 = u.pm * BM + wr * 64 + fr, col0 = u.pn * HALF + wc * 32 + 8 * fq;
; #pragma unroll
;         for (int ai = 0; ai < 2; ++ai)
; #pragma unroll
;             for (int m = 0; m < 4; ++m) { bf16_t* rowp = O + (size_t)(row0 + ai * HALF + m * 16) * DFF + col0;
;                 f32x4 v[2];
; #pragma unroll
;                 for (int n = 0; n < 2; ++n)
; #pragma unroll
;                     for (int j = 0; j < 4; ++j) { const float gt = acc[ai][0][m][n][j], up = acc[ai][1][m][n][j]; v[n][j] = gt * sigmoidf_(gt) * up; }
;                 store8_nt(rowp, v[0], v[1]); }
	v_pk_add_f32 v[172:173], v[172:173], 1.0 op_sel_hi:[1,0]
	v_pk_add_f32 v[174:175], v[174:175], 1.0 op_sel_hi:[1,0]
	v_rcp_f32_e32 v168, v168
	v_rcp_f32_e32 v169, v169
	v_rcp_f32_e32 v170, v170
	v_rcp_f32_e32 v171, v171
	v_rcp_f32_e32 v172, v172
	v_rcp_f32_e32 v173, v173
	v_rcp_f32_e32 v174, v174
	v_rcp_f32_e32 v175, v175
	v_pk_mul_f32 v[76:77], v[76:77], v[168:169]
	v_pk_mul_f32 v[78:79], v[78:79], v[170:171]
	v_pk_mul_f32 v[68:69], v[68:69], v[172:173]
	v_pk_mul_f32 v[70:71], v[70:71], v[174:175]
	v_pk_mul_f32 v[76:77], v[72:73], v[76:77]
	v_pk_mul_f32 v[78:79], v[74:75], v[78:79]
	v_pk_mul_f32 v[68:69], v[64:65], v[68:69]
	v_pk_mul_f32 v[70:71], v[66:67], v[70:71]
	v_cvt_pk_bf16_f32 v180, v76, v77
	v_cvt_pk_bf16_f32 v181, v78, v79
	v_cvt_pk_bf16_f32 v182, v68, v69
	v_cvt_pk_bf16_f32 v183, v70, v71
	global_store_dwordx4 v[184:185], v[180:183], off nt
	v_add_u32_e32 v153, 0x80, v152
	v_mad_i64_i32 v[156:157], s[10:11], v153, s82, v[144:145]
	v_pk_mul_f32 v[160:161], v[60:61], s[98:99]
	v_pk_mul_f32 v[162:163], v[62:63], s[98:99]
	v_pk_mul_f32 v[164:165], v[52:53], s[98:99]
	v_pk_mul_f32 v[166:167], v[54:55], s[98:99]
	v_exp_f32_e32 v160, v160
	v_exp_f32_e32 v161, v161
	v_exp_f32_e32 v162, v162
	v_exp_f32_e32 v163, v163
	v_exp_f32_e32 v164, v164
	v_exp_f32_e32 v165, v165
	v_exp_f32_e32 v166, v166
	v_exp_f32_e32 v167, v167
	v_lshl_add_u64 v[156:157], v[156:157], 0, v[158:159]
	v_pk_add_f32 v[160:161], v[160:161], 1.0 op_sel_hi:[1,0]
	v_pk_add_f32 v[162:163], v[162:163], 1.0 op_sel_hi:[1,0]
	v_pk_add_f32 v[164:165], v[164:165], 1.0 op_sel_hi:[1,0]
	v_pk_add_f32 v[166:167], v[166:167], 1.0 op_sel_hi:[1,0]
	v_rcp_f32_e32 v160, v160
	v_rcp_f32_e32 v161, v161
	v_rcp_f32_e32 v162, v162
	v_rcp_f32_e32 v163, v163
	v_rcp_f32_e32 v164, v164
	v_rcp_f32_e32 v165, v165
	v_rcp_f32_e32 v166, v166
	v_rcp_f32_e32 v167, v167
	v_pk_mul_f32 v[60:61], v[60:61], v[160:161]
	v_pk_mul_f32 v[62:63], v[62:63], v[162:163]
	v_pk_mul_f32 v[52:53], v[52:53], v[164:165]
	v_pk_mul_f32 v[54:55], v[54:55], v[166:167]
	v_pk_mul_f32 v[60:61], v[56:57], v[60:61]
	v_pk_mul_f32 v[62:63], v[58:59], v[62:63]
	v_pk_mul_f32 v[52:53], v[48:49], v[52:53]
	v_pk_mul_f32 v[54:55], v[50:51], v[54:55]
	v_cvt_pk_bf16_f32 v176, v60, v61
	v_cvt_pk_bf16_f32 v177, v62, v63
	v_cvt_pk_bf16_f32 v178, v52, v53
	v_cvt_pk_bf16_f32 v179, v54, v55
	global_store_dwordx4 v[156:157], v[176:179], off nt
	v_add_u32_e32 v153, 0x90, v152
	v_mad_i64_i32 v[184:185], s[10:11], v153, s82, v[144:145]
	v_pk_mul_f32 v[168:169], v[44:45], s[98:99]
	v_pk_mul_f32 v[170:171], v[46:47], s[98:99]
	v_pk_mul_f32 v[172:173], v[36:37], s[98:99]
	v_pk_mul_f32 v[174:175], v[38:39], s[98:99]
	v_exp_f32_e32 v168, v168
	v_exp_f32_e32 v169, v169
	v_exp_f32_e32 v170, v170
	v_exp_f32_e32 v171, v171
	v_exp_f32_e32 v172, v172
	v_exp_f32_e32 v173, v173
	v_exp_f32_e32 v174, v174
	v_exp_f32_e32 v175, v175
	v_lshl_add_u64 v[184:185], v[184:185], 0, v[158:159]
	v_pk_add_f32 v[168:169], v[168:169], 1.0 op_sel_hi:[1,0]
	v_pk_add_f32 v[170:171], v[170:171], 1.0 op_sel_hi:[1,0]
	v_pk_add_f32 v[172:173], v[172:173], 1.0 op_sel_hi:[1,0]
	v_pk_add_f32 v[174:175], v[174:175], 1.0 op_sel_hi:[1,0]
	v_rcp_f32_e32 v168, v168
	v_rcp_f32_e32 v169, v169
	v_rcp_f32_e32 v170, v170
	v_rcp_f32_e32 v171, v171
	v_rcp_f32_e32 v172, v172
	v_rcp_f32_e32 v173, v173
	v_rcp_f32_e32 v174, v174
	v_rcp_f32_e32 v175, v175
	v_pk_mul_f32 v[44:45], v[44:45], v[168:169]
	v_pk_mul_f32 v[46:47], v[46:47], v[170:171]
	v_pk_mul_f32 v[36:37], v[36:37], v[172:173]
	v_pk_mul_f32 v[38:39], v[38:39], v[174:175]
	v_pk_mul_f32 v[44:45], v[40:41], v[44:45]
	v_pk_mul_f32 v[46:47], v[42:43], v[46:47]
	v_pk_mul_f32 v[36:37], v[32:33], v[36:37]
	v_pk_mul_f32 v[38:39], v[34:35], v[38:39]
	v_cvt_pk_bf16_f32 v180, v44, v45
	v_cvt_pk_bf16_f32 v181, v46, v47
	v_cvt_pk_bf16_f32 v182, v36, v37
	v_cvt_pk_bf16_f32 v183, v38, v39
	global_store_dwordx4 v[184:185], v[180:183], off nt
	v_add_u32_e32 v153, 0xa0, v152
	v_mad_i64_i32 v[156:157], s[10:11], v153, s82, v[144:145]
	v_pk_mul_f32 v[160:161], v[28:29], s[98:99]
	v_pk_mul_f32 v[162:163], v[30:31], s[98:99]
	v_pk_mul_f32 v[164:165], v[20:21], s[98:99]
	v_pk_mul_f32 v[166:167], v[22:23], s[98:99]
	v_exp_f32_e32 v160, v160
	v_exp_f32_e32 v161, v161
	v_exp_f32_e32 v162, v162
	v_exp_f32_e32 v163, v163
	v_exp_f32_e32 v164, v164
	v_exp_f32_e32 v165, v165
	v_exp_f32_e32 v166, v166
	v_exp_f32_e32 v167, v167
	v_lshl_add_u64 v[156:157], v[156:157], 0, v[158:159]
	v_pk_add_f32 v[160:161], v[160:161], 1.0 op_sel_hi:[1,0]
	v_pk_add_f32 v[162:163], v[162:163], 1.0 op_sel_hi:[1,0]
	v_pk_add_f32 v[164:165], v[164:165], 1.0 op_sel_hi:[1,0]
	v_pk_add_f32 v[166:167], v[166:167], 1.0 op_sel_hi:[1,0]
	v_rcp_f32_e32 v160, v160
	v_rcp_f32_e32 v161, v161
	v_rcp_f32_e32 v162, v162
	v_rcp_f32_e32 v163, v163
	v_rcp_f32_e32 v164, v164
	v_rcp_f32_e32 v165, v165
	v_rcp_f32_e32 v166, v166
	v_rcp_f32_e32 v167, v167
	v_pk_mul_f32 v[28:29], v[28:29], v[160:161]
	v_pk_mul_f32 v[30:31], v[30:31], v[162:163]
	v_pk_mul_f32 v[20:21], v[20:21], v[164:165]
	v_pk_mul_f32 v[22:23], v[22:23], v[166:167]
	v_pk_mul_f32 v[28:29], v[24:25], v[28:29]
	v_pk_mul_f32 v[30:31], v[26:27], v[30:31]
	v_pk_mul_f32 v[20:21], v[16:17], v[20:21]
	v_pk_mul_f32 v[22:23], v[18:19], v[22:23]
	v_cvt_pk_bf16_f32 v176, v28, v29
	v_cvt_pk_bf16_f32 v177, v30, v31
	v_cvt_pk_bf16_f32 v178, v20, v21
	v_cvt_pk_bf16_f32 v179, v22, v23
	global_store_dwordx4 v[156:157], v[176:179], off nt
	v_add_u32_e32 v153, 0xb0, v152
	v_mad_i64_i32 v[184:185], s[10:11], v153, s82, v[144:145]
	v_pk_mul_f32 v[168:169], v[12:13], s[98:99]
	v_pk_mul_f32 v[170:171], v[14:15], s[98:99]
	v_pk_mul_f32 v[172:173], v[4:5], s[98:99]
	v_pk_mul_f32 v[174:175], v[6:7], s[98:99]
	v_exp_f32_e32 v168, v168
	v_exp_f32_e32 v169, v169
	v_exp_f32_e32 v170, v170
	v_exp_f32_e32 v171, v171
	v_exp_f32_e32 v172, v172
	v_exp_f32_e32 v173, v173
	v_exp_f32_e32 v174, v174
	v_exp_f32_e32 v175, v175
	v_lshl_add_u64 v[184:185], v[184:185], 0, v[158:159]
	v_pk_add_f32 v[168:169], v[168:169], 1.0 op_sel_hi:[1,0]
	v_pk_add_f32 v[170:171], v[170:171], 1.0 op_sel_hi:[1,0]
	v_pk_add_f32 v[172:173], v[172:173], 1.0 op_sel_hi:[1,0]
	v_pk_add_f32 v[174:175], v[174:175], 1.0 op_sel_hi:[1,0]
	v_rcp_f32_e32 v168, v168
	v_rcp_f32_e32 v169, v169
	v_rcp_f32_e32 v170, v170
	v_rcp_f32_e32 v171, v171
	v_rcp_f32_e32 v172, v172
	v_rcp_f32_e32 v173, v173
	v_rcp_f32_e32 v174, v174
	v_rcp_f32_e32 v175, v175
	v_pk_mul_f32 v[12:13], v[12:13], v[168:169]
	v_pk_mul_f32 v[14:15], v[14:15], v[170:171]
	v_pk_mul_f32 v[4:5], v[4:5], v[172:173]
	v_pk_mul_f32 v[6:7], v[6:7], v[174:175]
	v_pk_mul_f32 v[12:13], v[8:9], v[12:13]
	v_pk_mul_f32 v[14:15], v[10:11], v[14:15]
	v_pk_mul_f32 v[4:5], v[0:1], v[4:5]
	v_pk_mul_f32 v[6:7], v[2:3], v[6:7]
	v_cvt_pk_bf16_f32 v180, v12, v13
	v_cvt_pk_bf16_f32 v181, v14, v15
	v_cvt_pk_bf16_f32 v182, v4, v5
	v_cvt_pk_bf16_f32 v183, v6, v7
	global_store_dwordx4 v[184:185], v[180:183], off nt
	s_mov_b64 s[10:11], s[64:65]
	s_cbranch_vccnz .LBB0_341

; DEVINL float sigmoidf_(float z) { return __builtin_amdgcn_rcpf(1.0f + __expf(-z)); }
;     DEVINL void operator()(AccRef acc, const Unit& u, int wr, int wc, int fr, int fq) const {
;         const int row0 = u.pm * BM + wr * 64 + fr, col0 = u.pn * HALF + wc * 32 + 8 * fq;
; #pragma unroll
;         for (int ai = 0; ai < 2; ++ai)
; #pragma unroll
;             for (int m = 0; m < 4; ++m) { bf16_t* rowp = O + (size_t)(row0 + ai * HALF + m * 16) * DFF + col0;
;                 f32x4 v[2];
; #pragma unroll
;                 for (int n = 0; n < 2; ++n)
; #pragma unroll
;                     for (int j = 0; j < 4; ++j) { const float gt = acc[ai][0][m][n][j], up = acc[ai][1][m][n][j]; v[n][j] = gt * sigmoidf_(gt) * up; }
;                 store8_nt(rowp, v[0], v[1]); }
.LBB0_1770:
	v_lshl_or_b32 v154, s50, 7, v148
	v_lshl_add_u32 v152, s16, 8, v146
	v_ashrrev_i32_e32 v155, 31, v154
	v_mov_b64_e32 v[144:145], s[90:91]
	v_lshlrev_b64 v[158:159], 1, v[154:155]
	s_and_b64 vcc, exec, s[2:3]
	s_mov_b32 s50, s8
	s_mov_b32 s16, s10
	s_mov_b64 s[26:27], s[14:15]
	s_mov_b32 s98, 0xbfb8aa3b
	s_mov_b32 s99, 0xbfb8aa3b
	v_mad_i64_i32 v[156:157], s[24:25], v152, s49, v[144:145]
	v_pk_mul_f32 v[160:161], v[124:125], s[98:99]
	v_pk_mul_f32 v[162:163], v[126:127], s[98:99]
	v_pk_mul_f32 v[164:165], v[116:117], s[98:99]
	v_pk_mul_f32 v[166:167], v[118:119], s[98:99]
	v_exp_f32_e32 v160, v160
	v_exp_f32_e32 v161, v161
	v_exp_f32_e32 v162, v162
	v_exp_f32_e32 v163, v163
	v_exp_f32_e32 v164, v164
	v_exp_f32_e32 v165, v165
	v_exp_f32_e32 v166, v166
	v_exp_f32_e32 v167, v167
	v_lshl_add_u64 v[156:157], v[156:157], 0, v[158:159]
	v_pk_add_f32 v[160:161], v[160:161], 1.0 op_sel_hi:[1,0]
	v_pk_add_f32 v[162:163], v[162:163], 1.0 op_sel_hi:[1,0]
	v_pk_add_f32 v[164:165], v[164:165], 1.0 op_sel_hi:[1,0]
	v_pk_add_f32 v[166:167], v[166:167], 1.0 op_sel_hi:[1,0]
	v_rcp_f32_e32 v160, v160
	v_rcp_f32_e32 v161, v161
	v_rcp_f32_e32 v162, v162
	v_rcp_f32_e32 v163, v163
	v_rcp_f32_e32 v164, v164
	v_rcp_f32_e32 v165, v165
	v_rcp_f32_e32 v166, v166
	v_rcp_f32_e32 v167, v167
	v_pk_mul_f32 v[124:125], v[124:125], v[160:161]
	v_pk_mul_f32 v[126:127], v[126:127], v[162:163]
	v_pk_mul_f32 v[116:117], v[116:117], v[164:165]
	v_pk_mul_f32 v[118:119], v[118:119], v[166:167]
	v_pk_mul_f32 v[124:125], v[120:121], v[124:125]
	v_pk_mul_f32 v[126:127], v[122:123], v[126:127]
	v_pk_mul_f32 v[116:117], v[112:113], v[116:117]
	v_pk_mul_f32 v[118:119], v[114:115], v[118:119]
	v_cvt_pk_bf16_f32 v176, v124, v125
	v_cvt_pk_bf16_f32 v177, v126, v127
	v_cvt_pk_bf16_f32 v178, v116, v117
	v_cvt_pk_bf16_f32 v179, v118, v119
	global_store_dwordx4 v[156:157], v[176:179], off nt
	v_add_u32_e32 v153, 0x10, v152
	v_mad_i64_i32 v[184:185], s[24:25], v153, s49, v[144:145]
	v_pk_mul_f32 v[168:169], v[108:109], s[98:99]
	v_pk_mul_f32 v[170:171], v[110:111], s[98:99]
	v_pk_mul_f32 v[172:173], v[100:101], s[98:99]
	v_pk_mul_f32 v[174:175], v[102:103], s[98:99]
	v_exp_f32_e32 v168, v168
	v_exp_f32_e32 v169, v169
	v_exp_f32_e32 v170, v170
	v_exp_f32_e32 v171, v171
	v_exp_f32_e32 v172, v172
	v_exp_f32_e32 v173, v173
	v_exp_f32_e32 v174, v174
	v_exp_f32_e32 v175, v175
	v_lshl_add_u64 v[184:185], v[184:185], 0, v[158:159]
	v_pk_add_f32 v[168:169], v[168:169], 1.0 op_sel_hi:[1,0]
	v_pk_add_f32 v[170:171], v[170:171], 1.0 op_sel_hi:[1,0]
	v_pk_add_f32 v[172:173], v[172:173], 1.0 op_sel_hi:[1,0]
	v_pk_add_f32 v[174:175], v[174:175], 1.0 op_sel_hi:[1,0]
	v_rcp_f32_e32 v168, v168
	v_rcp_f32_e32 v169, v169
	v_rcp_f32_e32 v170, v170
	v_rcp_f32_e32 v171, v171
	v_rcp_f32_e32 v172, v172
	v_rcp_f32_e32 v173, v173
	v_rcp_f32_e32 v174, v174
	v_rcp_f32_e32 v175, v175
	v_pk_mul_f32 v[108:109], v[108:109], v[168:169]
	v_pk_mul_f32 v[110:111], v[110:111], v[170:171]
	v_pk_mul_f32 v[100:101], v[100:101], v[172:173]
	v_pk_mul_f32 v[102:103], v[102:103], v[174:175]
	v_pk_mul_f32 v[108:109], v[104:105], v[108:109]
	v_pk_mul_f32 v[110:111], v[106:107], v[110:111]
	v_pk_mul_f32 v[100:101], v[96:97], v[100:101]
	v_pk_mul_f32 v[102:103], v[98:99], v[102:103]
	v_cvt_pk_bf16_f32 v180, v108, v109
	v_cvt_pk_bf16_f32 v181, v110, v111
	v_cvt_pk_bf16_f32 v182, v100, v101
	v_cvt_pk_bf16_f32 v183, v102, v103
	global_store_dwordx4 v[184:185], v[180:183], off nt
	v_add_u32_e32 v153, 0x20, v152
	v_mad_i64_i32 v[156:157], s[24:25], v153, s49, v[144:145]
	v_pk_mul_f32 v[160:161], v[92:93], s[98:99]
	v_pk_mul_f32 v[162:163], v[94:95], s[98:99]
	v_pk_mul_f32 v[164:165], v[84:85], s[98:99]
	v_pk_mul_f32 v[166:167], v[86:87], s[98:99]
	v_exp_f32_e32 v160, v160
	v_exp_f32_e32 v161, v161
	v_exp_f32_e32 v162, v162
	v_exp_f32_e32 v163, v163
	v_exp_f32_e32 v164, v164
	v_exp_f32_e32 v165, v165
	v_exp_f32_e32 v166, v166
	v_exp_f32_e32 v167, v167
	v_lshl_add_u64 v[156:157], v[156:157], 0, v[158:159]
	v_pk_add_f32 v[160:161], v[160:161], 1.0 op_sel_hi:[1,0]
	v_pk_add_f32 v[162:163], v[162:163], 1.0 op_sel_hi:[1,0]
	v_pk_add_f32 v[164:165], v[164:165], 1.0 op_sel_hi:[1,0]
	v_pk_add_f32 v[166:167], v[166:167], 1.0 op_sel_hi:[1,0]
	v_rcp_f32_e32 v160, v160
	v_rcp_f32_e32 v161, v161
	v_rcp_f32_e32 v162, v162
	v_rcp_f32_e32 v163, v163
	v_rcp_f32_e32 v164, v164
	v_rcp_f32_e32 v165, v165
	v_rcp_f32_e32 v166, v166
	v_rcp_f32_e32 v167, v167
	v_pk_mul_f32 v[92:93], v[92:93], v[160:161]
	v_pk_mul_f32 v[94:95], v[94:95], v[162:163]
	v_pk_mul_f32 v[84:85], v[84:85], v[164:165]
	v_pk_mul_f32 v[86:87], v[86:87], v[166:167]
	v_pk_mul_f32 v[92:93], v[88:89], v[92:93]
	v_pk_mul_f32 v[94:95], v[90:91], v[94:95]
	v_pk_mul_f32 v[84:85], v[80:81], v[84:85]
	v_pk_mul_f32 v[86:87], v[82:83], v[86:87]
	v_cvt_pk_bf16_f32 v176, v92, v93
	v_cvt_pk_bf16_f32 v177, v94, v95
	v_cvt_pk_bf16_f32 v178, v84, v85
	v_cvt_pk_bf16_f32 v179, v86, v87
	global_store_dwordx4 v[156:157], v[176:179], off nt
	v_add_u32_e32 v153, 0x30, v152
	v_mad_i64_i32 v[184:185], s[24:25], v153, s49, v[144:145]
	v_pk_mul_f32 v[168:169], v[76:77], s[98:99]
	v_pk_mul_f32 v[170:171], v[78:79], s[98:99]
	v_pk_mul_f32 v[172:173], v[68:69], s[98:99]
	v_pk_mul_f32 v[174:175], v[70:71], s[98:99]
	v_exp_f32_e32 v168, v168
	v_exp_f32_e32 v169, v169
	v_exp_f32_e32 v170, v170
	v_exp_f32_e32 v171, v171
	v_exp_f32_e32 v172, v172
	v_exp_f32_e32 v173, v173
	v_exp_f32_e32 v174, v174
	v_exp_f32_e32 v175, v175
	v_lshl_add_u64 v[184:185], v[184:185], 0, v[158:159]
	v_pk_add_f32 v[168:169], v[168:169], 1.0 op_sel_hi:[1,0]
	v_pk_add_f32 v[170:171], v[170:171], 1.0 op_sel_hi:[1,0]
; DEVINL unsigned cvt_pk_bf16(float lo, float hi) { const f32x2 v = {lo, hi}; return __builtin_bit_cast(unsigned, __builtin_convertvector(v, bf16x2_t)); }
; DEVINL float sigmoidf_(float z) { return __builtin_amdgcn_rcpf(1.0f + __expf(-z)); }
; DEVINL void store8(bf16_t* p, f32x4 v0, f32x4 v1) {
;     u32x4 w; w.x = cvt_pk_bf16(v0[0], v0[1]); w.y = cvt_pk_bf16(v0[2], v0[3]); w.z = cvt_pk_bf16(v1[0], v1[1]); w.w = cvt_pk_bf16(v1[2], v1[3]);
;     *(u32x4*)p = w;
; }
; DEVINL void store8_nt(bf16_t* p, f32x4 v0, f32x4 v1) {
;     u32x4 w; w.x = cvt_pk_bf16(v0[0], v0[1]); w.y = cvt_pk_bf16(v0[2], v0[3]); w.z = cvt_pk_bf16(v1[0], v1[1]); w.w = cvt_pk_bf16(v1[2], v1[3]);
;     __builtin_nontemporal_store(w, (u32x4*)p);
; }
;     DEVINL void operator()(AccRef acc, const Unit& u, int wr, int wc, int fr, int fq) const {
;     ...
;         for (int ai = 0; ai < 2; ++ai)
; #pragma unroll
;             for (int m = 0; m < 4; ++m) { bf16_t* rowp = O + (size_t)(row0 + ai * HALF + m * 16) * DFF + col0;
;                 f32x4 v[2];
; #pragma unroll
;                 for (int n = 0; n < 2; ++n)
; #pragma unroll
;                     for (int j = 0; j < 4; ++j) { const float gt = acc[ai][0][m][n][j], up = acc[ai][1][m][n][j]; v[n][j] = gt * sigmoidf_(gt) * up; }
;                 store8_nt(rowp, v[0], v[1]); }
	v_pk_add_f32 v[172:173], v[172:173], 1.0 op_sel_hi:[1,0]
	v_pk_add_f32 v[174:175], v[174:175], 1.0 op_sel_hi:[1,0]
	v_rcp_f32_e32 v168, v168
	v_rcp_f32_e32 v169, v169
	v_rcp_f32_e32 v170, v170
	v_rcp_f32_e32 v171, v171
	v_rcp_f32_e32 v172, v172
	v_rcp_f32_e32 v173, v173
	v_rcp_f32_e32 v174, v174
	v_rcp_f32_e32 v175, v175
	v_pk_mul_f32 v[76:77], v[76:77], v[168:169]
	v_pk_mul_f32 v[78:79], v[78:79], v[170:171]
	v_pk_mul_f32 v[68:69], v[68:69], v[172:173]
	v_pk_mul_f32 v[70:71], v[70:71], v[174:175]
	v_pk_mul_f32 v[76:77], v[72:73], v[76:77]
	v_pk_mul_f32 v[78:79], v[74:75], v[78:79]
	v_pk_mul_f32 v[68:69], v[64:65], v[68:69]
	v_pk_mul_f32 v[70:71], v[66:67], v[70:71]
	v_cvt_pk_bf16_f32 v180, v76, v77
	v_cvt_pk_bf16_f32 v181, v78, v79
	v_cvt_pk_bf16_f32 v182, v68, v69
	v_cvt_pk_bf16_f32 v183, v70, v71
	global_store_dwordx4 v[184:185], v[180:183], off nt
	v_add_u32_e32 v153, 0x80, v152
	v_mad_i64_i32 v[156:157], s[24:25], v153, s49, v[144:145]
	v_pk_mul_f32 v[160:161], v[60:61], s[98:99]
	v_pk_mul_f32 v[162:163], v[62:63], s[98:99]
	v_pk_mul_f32 v[164:165], v[52:53], s[98:99]
	v_pk_mul_f32 v[166:167], v[54:55], s[98:99]
	v_exp_f32_e32 v160, v160
	v_exp_f32_e32 v161, v161
	v_exp_f32_e32 v162, v162
	v_exp_f32_e32 v163, v163
	v_exp_f32_e32 v164, v164
	v_exp_f32_e32 v165, v165
	v_exp_f32_e32 v166, v166
	v_exp_f32_e32 v167, v167
	v_lshl_add_u64 v[156:157], v[156:157], 0, v[158:159]
	v_pk_add_f32 v[160:161], v[160:161], 1.0 op_sel_hi:[1,0]
	v_pk_add_f32 v[162:163], v[162:163], 1.0 op_sel_hi:[1,0]
	v_pk_add_f32 v[164:165], v[164:165], 1.0 op_sel_hi:[1,0]
	v_pk_add_f32 v[166:167], v[166:167], 1.0 op_sel_hi:[1,0]
	v_rcp_f32_e32 v160, v160
	v_rcp_f32_e32 v161, v161
	v_rcp_f32_e32 v162, v162
	v_rcp_f32_e32 v163, v163
	v_rcp_f32_e32 v164, v164
	v_rcp_f32_e32 v165, v165
	v_rcp_f32_e32 v166, v166
	v_rcp_f32_e32 v167, v167
	v_pk_mul_f32 v[60:61], v[60:61], v[160:161]
	v_pk_mul_f32 v[62:63], v[62:63], v[162:163]
	v_pk_mul_f32 v[52:53], v[52:53], v[164:165]
	v_pk_mul_f32 v[54:55], v[54:55], v[166:167]
	v_pk_mul_f32 v[60:61], v[56:57], v[60:61]
	v_pk_mul_f32 v[62:63], v[58:59], v[62:63]
	v_pk_mul_f32 v[52:53], v[48:49], v[52:53]
	v_pk_mul_f32 v[54:55], v[50:51], v[54:55]
	v_cvt_pk_bf16_f32 v176, v60, v61
	v_cvt_pk_bf16_f32 v177, v62, v63
	v_cvt_pk_bf16_f32 v178, v52, v53
	v_cvt_pk_bf16_f32 v179, v54, v55
	global_store_dwordx4 v[156:157], v[176:179], off nt
	v_add_u32_e32 v153, 0x90, v152
	v_mad_i64_i32 v[184:185], s[24:25], v153, s49, v[144:145]
	v_pk_mul_f32 v[168:169], v[44:45], s[98:99]
	v_pk_mul_f32 v[170:171], v[46:47], s[98:99]
	v_pk_mul_f32 v[172:173], v[36:37], s[98:99]
	v_pk_mul_f32 v[174:175], v[38:39], s[98:99]
	v_exp_f32_e32 v168, v168
	v_exp_f32_e32 v169, v169
	v_exp_f32_e32 v170, v170
	v_exp_f32_e32 v171, v171
	v_exp_f32_e32 v172, v172
	v_exp_f32_e32 v173, v173
	v_exp_f32_e32 v174, v174
	v_exp_f32_e32 v175, v175
	v_lshl_add_u64 v[184:185], v[184:185], 0, v[158:159]
	v_pk_add_f32 v[168:169], v[168:169], 1.0 op_sel_hi:[1,0]
	v_pk_add_f32 v[170:171], v[170:171], 1.0 op_sel_hi:[1,0]
	v_pk_add_f32 v[172:173], v[172:173], 1.0 op_sel_hi:[1,0]
	v_pk_add_f32 v[174:175], v[174:175], 1.0 op_sel_hi:[1,0]
	v_rcp_f32_e32 v168, v168
	v_rcp_f32_e32 v169, v169
	v_rcp_f32_e32 v170, v170
	v_rcp_f32_e32 v171, v171
	v_rcp_f32_e32 v172, v172
	v_rcp_f32_e32 v173, v173
	v_rcp_f32_e32 v174, v174
	v_rcp_f32_e32 v175, v175
	v_pk_mul_f32 v[44:45], v[44:45], v[168:169]
	v_pk_mul_f32 v[46:47], v[46:47], v[170:171]
	v_pk_mul_f32 v[36:37], v[36:37], v[172:173]
	v_pk_mul_f32 v[38:39], v[38:39], v[174:175]
	v_pk_mul_f32 v[44:45], v[40:41], v[44:45]
	v_pk_mul_f32 v[46:47], v[42:43], v[46:47]
	v_pk_mul_f32 v[36:37], v[32:33], v[36:37]
	v_pk_mul_f32 v[38:39], v[34:35], v[38:39]
	v_cvt_pk_bf16_f32 v180, v44, v45
	v_cvt_pk_bf16_f32 v181, v46, v47
	v_cvt_pk_bf16_f32 v182, v36, v37
	v_cvt_pk_bf16_f32 v183, v38, v39
	global_store_dwordx4 v[184:185], v[180:183], off nt
	v_add_u32_e32 v153, 0xa0, v152
	v_mad_i64_i32 v[156:157], s[24:25], v153, s49, v[144:145]
	v_pk_mul_f32 v[160:161], v[28:29], s[98:99]
	v_pk_mul_f32 v[162:163], v[30:31], s[98:99]
	v_pk_mul_f32 v[164:165], v[20:21], s[98:99]
	v_pk_mul_f32 v[166:167], v[22:23], s[98:99]
	v_exp_f32_e32 v160, v160
	v_exp_f32_e32 v161, v161
	v_exp_f32_e32 v162, v162
	v_exp_f32_e32 v163, v163
	v_exp_f32_e32 v164, v164
	v_exp_f32_e32 v165, v165
	v_exp_f32_e32 v166, v166
	v_exp_f32_e32 v167, v167
	v_lshl_add_u64 v[156:157], v[156:157], 0, v[158:159]
	v_pk_add_f32 v[160:161], v[160:161], 1.0 op_sel_hi:[1,0]
	v_pk_add_f32 v[162:163], v[162:163], 1.0 op_sel_hi:[1,0]
	v_pk_add_f32 v[164:165], v[164:165], 1.0 op_sel_hi:[1,0]
	v_pk_add_f32 v[166:167], v[166:167], 1.0 op_sel_hi:[1,0]
	v_rcp_f32_e32 v160, v160
	v_rcp_f32_e32 v161, v161
	v_rcp_f32_e32 v162, v162
	v_rcp_f32_e32 v163, v163
	v_rcp_f32_e32 v164, v164
	v_rcp_f32_e32 v165, v165
	v_rcp_f32_e32 v166, v166
	v_rcp_f32_e32 v167, v167
	v_pk_mul_f32 v[28:29], v[28:29], v[160:161]
	v_pk_mul_f32 v[30:31], v[30:31], v[162:163]
	v_pk_mul_f32 v[20:21], v[20:21], v[164:165]
	v_pk_mul_f32 v[22:23], v[22:23], v[166:167]
	v_pk_mul_f32 v[28:29], v[24:25], v[28:29]
	v_pk_mul_f32 v[30:31], v[26:27], v[30:31]
	v_pk_mul_f32 v[20:21], v[16:17], v[20:21]
	v_pk_mul_f32 v[22:23], v[18:19], v[22:23]
	v_cvt_pk_bf16_f32 v176, v28, v29
	v_cvt_pk_bf16_f32 v177, v30, v31
	v_cvt_pk_bf16_f32 v178, v20, v21
	v_cvt_pk_bf16_f32 v179, v22, v23
	global_store_dwordx4 v[156:157], v[176:179], off nt
	v_add_u32_e32 v153, 0xb0, v152
	v_mad_i64_i32 v[184:185], s[24:25], v153, s49, v[144:145]
	v_pk_mul_f32 v[168:169], v[12:13], s[98:99]
	v_pk_mul_f32 v[170:171], v[14:15], s[98:99]
	v_pk_mul_f32 v[172:173], v[4:5], s[98:99]
	v_pk_mul_f32 v[174:175], v[6:7], s[98:99]
	v_exp_f32_e32 v168, v168
	v_exp_f32_e32 v169, v169
	v_exp_f32_e32 v170, v170
	v_exp_f32_e32 v171, v171
	v_exp_f32_e32 v172, v172
	v_exp_f32_e32 v173, v173
	v_exp_f32_e32 v174, v174
	v_exp_f32_e32 v175, v175
	v_lshl_add_u64 v[184:185], v[184:185], 0, v[158:159]
	v_pk_add_f32 v[168:169], v[168:169], 1.0 op_sel_hi:[1,0]
	v_pk_add_f32 v[170:171], v[170:171], 1.0 op_sel_hi:[1,0]
	v_pk_add_f32 v[172:173], v[172:173], 1.0 op_sel_hi:[1,0]
	v_pk_add_f32 v[174:175], v[174:175], 1.0 op_sel_hi:[1,0]
	v_rcp_f32_e32 v168, v168
	v_rcp_f32_e32 v169, v169
	v_rcp_f32_e32 v170, v170
	v_rcp_f32_e32 v171, v171
	v_rcp_f32_e32 v172, v172
	v_rcp_f32_e32 v173, v173
	v_rcp_f32_e32 v174, v174
	v_rcp_f32_e32 v175, v175
	v_pk_mul_f32 v[12:13], v[12:13], v[168:169]
	v_pk_mul_f32 v[14:15], v[14:15], v[170:171]
	v_pk_mul_f32 v[4:5], v[4:5], v[172:173]
	v_pk_mul_f32 v[6:7], v[6:7], v[174:175]
	v_pk_mul_f32 v[12:13], v[8:9], v[12:13]
	v_pk_mul_f32 v[14:15], v[10:11], v[14:15]
	v_pk_mul_f32 v[4:5], v[0:1], v[4:5]
	v_pk_mul_f32 v[6:7], v[2:3], v[6:7]
	v_cvt_pk_bf16_f32 v180, v12, v13
	v_cvt_pk_bf16_f32 v181, v14, v15
	v_cvt_pk_bf16_f32 v182, v4, v5
	v_cvt_pk_bf16_f32 v183, v6, v7
	global_store_dwordx4 v[184:185], v[180:183], off nt
	s_mov_b64 s[24:25], s[12:13]
	s_cbranch_vccnz .LBB0_1776

; __global__ void __launch_bounds__(512) fwd_megakernel(Params p) {
	.amdhsa_kernel _Z14fwd_megakernel6Params
		.amdhsa_group_segment_fixed_size 16
		.amdhsa_private_segment_fixed_size 0
		.amdhsa_kernarg_size 1712
		.amdhsa_user_sgpr_count 2
		.amdhsa_user_sgpr_dispatch_ptr 0
		.amdhsa_user_sgpr_queue_ptr 0
		.amdhsa_user_sgpr_kernarg_segment_ptr 1
		.amdhsa_user_sgpr_dispatch_id 0
		.amdhsa_user_sgpr_kernarg_preload_length 0
		.amdhsa_user_sgpr_kernarg_preload_offset 0
		.amdhsa_user_sgpr_private_segment_size 0
		.amdhsa_uses_dynamic_stack 0
		.amdhsa_enable_private_segment 0
		.amdhsa_system_sgpr_workgroup_id_x 1
		.amdhsa_system_sgpr_workgroup_id_y 0
		.amdhsa_system_sgpr_workgroup_id_z 0
		.amdhsa_system_sgpr_workgroup_info 0
		.amdhsa_system_vgpr_workitem_id 2
		.amdhsa_next_free_vgpr 252
		.amdhsa_next_free_sgpr 102
		.amdhsa_accum_offset 252
		.amdhsa_reserve_vcc 1
		.amdhsa_float_round_mode_32 0
		.amdhsa_float_round_mode_16_64 0
		.amdhsa_float_denorm_mode_32 3
		.amdhsa_float_denorm_mode_16_64 3
		.amdhsa_dx10_clamp 1
		.amdhsa_ieee_mode 1
		.amdhsa_fp16_overflow 0
		.amdhsa_tg_split 0
		.amdhsa_exception_fp_ieee_invalid_op 0
		.amdhsa_exception_fp_denorm_src 0
		.amdhsa_exception_fp_ieee_div_zero 0
		.amdhsa_exception_fp_ieee_overflow 0
		.amdhsa_exception_fp_ieee_underflow 0
		.amdhsa_exception_fp_ieee_inexact 0
		.amdhsa_exception_int_div_zero 0
	.end_amdhsa_kernel

; __global__ void __launch_bounds__(512) fwd_megakernel(Params p) {
amdhsa.kernels:
  - .agpr_count:     0
    .args:
      - .offset:         0
        .size:           1456
        .value_kind:     by_value
      - .offset:         1456
        .size:           4
        .value_kind:     hidden_block_count_x
      - .offset:         1460
        .size:           4
        .value_kind:     hidden_block_count_y
      - .offset:         1464
        .size:           4
        .value_kind:     hidden_block_count_z
      - .offset:         1468
        .size:           2
        .value_kind:     hidden_group_size_x
      - .offset:         1470
        .size:           2
        .value_kind:     hidden_group_size_y
      - .offset:         1472
        .size:           2
        .value_kind:     hidden_group_size_z
      - .offset:         1474
        .size:           2
        .value_kind:     hidden_remainder_x
      - .offset:         1476
        .size:           2
        .value_kind:     hidden_remainder_y
      - .offset:         1478
        .size:           2
        .value_kind:     hidden_remainder_z
      - .offset:         1496
        .size:           8
        .value_kind:     hidden_global_offset_x
      - .offset:         1504
        .size:           8
        .value_kind:     hidden_global_offset_y
      - .offset:         1512
        .size:           8
        .value_kind:     hidden_global_offset_z
      - .offset:         1520
        .size:           2
        .value_kind:     hidden_grid_dims
      - .offset:         1544
        .size:           8
        .value_kind:     hidden_multigrid_sync_arg
      - .offset:         1576
        .size:           4
        .value_kind:     hidden_dynamic_lds_size
    .group_segment_fixed_size: 16
    .kernarg_segment_align: 8
    .kernarg_segment_size: 1712
    .language:       OpenCL C
    .language_version:
      - 2
      - 0
    .max_flat_workgroup_size: 512
    .name:           _Z14fwd_megakernel6Params
    .private_segment_fixed_size: 0
    .sgpr_count:     108
    .sgpr_spill_count: 70
    .symbol:         _Z14fwd_megakernel6Params.kd
    .uniform_work_group_size: 1
    .uses_dynamic_stack: false
    .vgpr_count:     252
    .vgpr_spill_count: 0
    .wavefront_size: 64
